# next chunk's f32->fp16 input conversion moved into the idle time of the 128 workgroups without a sixth unit in the chunk's last FFN-up phase
# speedup vs baseline: 1.0000x; 1.0000x over previous
; __global__ void __launch_bounds__(512, 2) mega_fwd(Args args) {
;     ...
;                     const bool last = (l == NLAYER - 1 && k == 8);
;                     pg8::Gemm g{ffn ? hb : mixb, WL + (k == 1 ? OFF_W1OUT : (k == 8 ? OFF_W2OUT : OFF_WOUT)), TC, D, ffn ? DFF : D, ffn ? DFF : D, ffn ? DFF : D, 0, 0};
;                     pg8::Order S; S.init(TC, D, 1, G, bx);
;                     const int nuse = (c * NLAYER + l) * 3 + sidx;
;                     pg8::EpiResidLN E{last ? X : nullptr, xb, args.in[sidx == 0 ? 6 : (sidx == 1 ? 13 : 17)] + l * D, args.in[sidx == 0 ? 7 : (sidx == 1 ? 14 : 18)] + l * D, ffn ? 0.5f : 1.0f,
;                                       (unsigned long long*)(ws + WS_CTL + CTL_XBUF), (unsigned*)(ws + WS_CTL + 16384), 32u * (unsigned)(nuse + 1)};
;                     pg8::gemm_phase(lds, g, S, E);
;                     if (last && c + 1 < NCHUNK) load_chunk = c + 1;
.LBB0_258:
.LBB0_259:
	s_cmp_lt_i32 s21, 55
	s_cselect_b64 s[4:5], -1, 0
	s_and_b64 s[4:5], s[24:25], s[4:5]
	s_add_i32 s6, s30, 1
	s_and_b64 s[4:5], s[4:5], exec
	s_mov_b32 s22, -1
	s_mov_b64 s[64:65], 0
	s_mov_b64 s[8:9], 0

; __global__ void __launch_bounds__(512, 2) mega_fwd(Args args) {
;     ...
;                 const int l = r / 9, k = r - l * 9;
;                 const bf16_t* WL = Wb + (size_t)l * W_LAYER_ELEMS;
;                 if (k == 0 || k == 7) {
;                     pg8::Gemm g{xb, WL + (k == 0 ? OFF_W1IN : OFF_W2IN), TC, 2 * DFF, D, D, D, 0, 0}; pg8::Order S; S.init(TC, 2 * DFF, 1, G, bx); pg8::EpiSwiglu E{hb, DFF}; for (int rep = 0; rep < REP_UP; ++rep) pg8::gemm_phase(lds, g, S, E);
;                     if (c == 0 && l == 0 && k == 0) {
;     ...
;         if (load_chunk >= 0) {
;             const float* xin = load_chunk < 2 ? args.in[0] + (size_t)load_chunk * TC * D : args.in[1] + (size_t)(load_chunk - 2) * TC * D;
;             bf16_t* xnext = (bf16_t*)(ws + ((load_chunk & 1) ? WS_XB : WS_X16));
.LBB0_420:
	s_mov_b32 s22, -1
	s_mov_b32 s100, 0
	v_readlane_b32 s101, v255, 43
	s_nop 1
	s_cmp_eq_u32 s101, 16
	s_cbranch_scc0 .Ltail_no
	s_cmp_lt_u32 s20, 71
	s_cbranch_scc0 .Ltail_no
	v_readlane_b32 s101, v254, 6
	s_nop 1
	s_bitcmp1_b32 s101, 7
	s_cbranch_scc0 .Ltail_no
	s_add_i32 s101, s20, 1
	s_mul_hi_u32 s101, s101, 0x38e38e39
	s_lshr_b32 s22, s101, 2
	s_mov_b32 s100, 1
.Ltail_no:
.LBB0_421:
	v_readlane_b32 s6, v255, 16
	v_readlane_b32 s26, v255, 18
	v_readlane_b32 s28, v255, 20
	v_readlane_b32 s30, v255, 22
	v_readlane_b32 s34, v255, 24
	v_readlane_b32 s36, v255, 26
	v_readlane_b32 s48, v255, 28
	v_readlane_b32 s50, v255, 30
	v_readlane_b32 s64, v255, 32
	v_readlane_b32 s66, v255, 34
	v_readlane_b32 s68, v255, 36
	v_readlane_b32 s70, v255, 38
	v_readlane_b32 s76, v255, 40
	s_mov_b64 s[8:9], 0
	v_readlane_b32 s7, v255, 17
	v_readlane_b32 s27, v255, 19
	v_readlane_b32 s29, v255, 21
	v_readlane_b32 s31, v255, 23
	v_readlane_b32 s35, v255, 25
	v_readlane_b32 s37, v255, 27
	v_readlane_b32 s49, v255, 29
	v_readlane_b32 s51, v255, 31
	v_readlane_b32 s65, v255, 33
	v_readlane_b32 s67, v255, 35
	v_readlane_b32 s69, v255, 37
	v_readlane_b32 s71, v255, 39
	v_readlane_b32 s77, v255, 41

; __global__ void __launch_bounds__(512, 2) mega_fwd(Args args) {
;     ...
;             load_chunk = 0;
.LBB0_456:
	s_mov_b32 s22, 0
	s_mov_b32 s100, 0

; __global__ void __launch_bounds__(512, 2) mega_fwd(Args args) {
;     ...
;         if (load_chunk >= 0) {
;             const float* xin = load_chunk < 2 ? args.in[0] + (size_t)load_chunk * TC * D : args.in[1] + (size_t)(load_chunk - 2) * TC * D;
;             bf16_t* xnext = (bf16_t*)(ws + ((load_chunk & 1) ? WS_XB : WS_X16));
;             for (int m0 = gw; m0 < TC; m0 += 4 * NGW) {
;                 f32x4 v[4][4];
.Ltail_next:
	s_cmp_eq_u32 s100, 1
	s_cbranch_scc0 .LBB0_471
	s_mov_b32 s100, 0
	v_readfirstlane_b32 s101, v196
	v_readlane_b32 s0, v254, 6
	s_nop 1
	s_lshr_b32 s101, s101, 6
	s_add_i32 s0, s0, s101
	s_addk_i32 s0, 0xff80
	s_branch .LBB0_465
